# v9b + attention loop: first three P.V MFMAs (and their V fragment reads) hoisted into the row-maximum section, their six exps spread over the following gaps
# speedup vs baseline: 1.0206x; 1.0027x over previous
.LBB0_1309:
	s_waitcnt lgkmcnt(7)
	v_mfma_f32_32x32x16_bf16 v[114:129], v[190:193], v[150:153], v[218:233]
	v_add_f32_e32 v98, v82, v83
	v_add_f32_e32 v98, v84, v98
	v_add_f32_e32 v98, v85, v98
	v_add_f32_e32 v98, v86, v98
	v_add_u32_e32 v247, s30, v246
	v_add_f32_e32 v98, v87, v98
	v_cvt_pk_bf16_f32 v158, v82, v83
	v_cvt_pk_bf16_f32 v159, v84, v85
	s_nop 0
	v_add_f32_e32 v82, v88, v98
	s_waitcnt lgkmcnt(6)
	v_mfma_f32_32x32x16_bf16 v[98:113], v[182:185], v[150:153], v[218:233]
	v_add_f32_e32 v82, v89, v82
	v_add_f32_e32 v82, v90, v82
	v_add_f32_e32 v82, v91, v82
	v_cvt_pk_bf16_f32 v160, v86, v87
	v_cvt_pk_bf16_f32 v161, v88, v89
	s_waitcnt lgkmcnt(5)
	v_mfma_f32_32x32x16_bf16 v[114:129], v[186:189], v[146:149], v[114:129]
	v_add_f32_e32 v82, v92, v82
	v_add_f32_e32 v82, v93, v82
	v_add_f32_e32 v82, v94, v82
	v_add_f32_e32 v82, v95, v82
	v_cvt_pk_bf16_f32 v154, v90, v91
	v_cvt_pk_bf16_f32 v155, v92, v93
	s_waitcnt lgkmcnt(4)
	v_mfma_f32_32x32x16_bf16 v[98:113], v[178:181], v[146:149], v[98:113]
	v_add_f32_e32 v82, v96, v82
	v_add_f32_e32 v82, v97, v82
	v_add_f32_e32 v82, v66, v82
	v_add_f32_e32 v86, v67, v82
	v_cvt_pk_bf16_f32 v156, v94, v95
	v_cvt_pk_bf16_f32 v157, v96, v97
	ds_read_b64_tr_b16 v[82:83], v247 offset:49152
	ds_read_b64_tr_b16 v[84:85], v247 offset:49664
	s_waitcnt lgkmcnt(5)
	v_mfma_f32_32x32x16_bf16 v[114:129], v[174:177], v[142:145], v[114:129]
	v_add_f32_e32 v86, v68, v86
	v_add_f32_e32 v86, v69, v86
	v_add_f32_e32 v86, v70, v86
	v_add_f32_e32 v86, v71, v86
	v_cvt_pk_bf16_f32 v138, v66, v67
	v_cvt_pk_bf16_f32 v139, v68, v69
	ds_read_b64_tr_b16 v[66:67], v247 offset:50176
	ds_read_b64_tr_b16 v[68:69], v247 offset:50688
	v_lshl_add_u64 v[188:189], v[214:215], 0, s[52:53]
	v_lshl_add_u64 v[92:93], v[188:189], 0, s[70:71]
	s_add_i32 s27, s91, s25
	s_mov_b32 s30, m0
	s_mov_b32 m0, s27
	s_nop 0
	global_load_lds_dwordx4 v[92:93], off
	s_mov_b32 m0, s30
	s_waitcnt lgkmcnt(6)
	v_mfma_f32_32x32x16_bf16 v[98:113], v[170:173], v[142:145], v[98:113]
	v_add_f32_e32 v86, v72, v86
	v_add_f32_e32 v86, v73, v86
	v_add_f32_e32 v86, v74, v86
	v_add_f32_e32 v86, v75, v86
	v_cvt_pk_bf16_f32 v140, v70, v71
	v_cvt_pk_bf16_f32 v141, v72, v73
	ds_read_b64_tr_b16 v[70:71], v247 offset:53248
	ds_read_b64_tr_b16 v[72:73], v247 offset:53760
	v_lshl_add_u64 v[92:93], v[188:189], 0, s[72:73]
	v_lshl_add_u64 v[186:187], v[216:217], 0, s[52:53]
	s_addk_i32 s27, 0x2000
	s_mov_b32 s30, m0
	s_mov_b32 m0, s27
	s_nop 0
	global_load_lds_dwordx4 v[92:93], off
	s_mov_b32 m0, s30
	s_waitcnt lgkmcnt(7)
	v_mfma_f32_32x32x16_bf16 v[114:129], v[166:169], v[134:137], v[114:129]
	v_add_f32_e32 v86, v76, v86
	v_add_f32_e32 v86, v77, v86
	v_add_f32_e32 v86, v78, v86
	v_add_f32_e32 v86, v79, v86
	v_cvt_pk_bf16_f32 v130, v74, v75
	v_cvt_pk_bf16_f32 v131, v76, v77
	ds_read_b64_tr_b16 v[74:75], v247 offset:54272
	ds_read_b64_tr_b16 v[76:77], v247 offset:54784
	v_lshl_add_u64 v[92:93], v[186:187], 0, s[74:75]
	s_add_i32 s27, s29, s24
	s_mov_b32 s30, m0
	s_mov_b32 m0, s27
	s_nop 0
	global_load_lds_dwordx4 v[92:93], off
	s_mov_b32 m0, s30
	s_waitcnt lgkmcnt(8)
	v_mfma_f32_32x32x16_bf16 v[98:113], v[162:165], v[134:137], v[98:113]
	v_add_f32_e32 v86, v80, v86
	v_add_f32_e32 v86, v81, v86
	v_add_f32_e32 v86, 0, v86
	v_cvt_pk_bf16_f32 v132, v78, v79
	v_cvt_pk_bf16_f32 v133, v80, v81
	v_lshl_add_u64 v[92:93], v[186:187], 0, s[76:77]
	s_addk_i32 s27, 0x2000
	s_mov_b32 s30, m0
	s_mov_b32 m0, s27
	s_nop 0
	global_load_lds_dwordx4 v[92:93], off
	s_mov_b32 m0, s30
	s_waitcnt lgkmcnt(6)
	v_mfma_f32_32x32x16_bf16 v[18:33], v[158:161], v[82:85], v[18:33]
	ds_read_b64_tr_b16 v[78:79], v247 offset:57344
	ds_read_b64_tr_b16 v[80:81], v247 offset:57856
	v_max_f32_e32 v94, v115, v115
	v_max_f32_e32 v95, v114, v114
	v_max_f32_e32 v94, v95, v94
	v_max3_f32 v95, v116, v117, v99
	v_max3_f32 v94, v94, v98, v100
	v_max3_f32 v94, v94, v101, v118
	v_max3_f32 v95, v95, v120, v121
	v_max3_f32 v94, v94, v119, v102
	v_max3_f32 v95, v95, v104, v105
	s_waitcnt lgkmcnt(6)
	v_mfma_f32_32x32x16_bf16 v[18:33], v[154:157], v[66:69], v[18:33]
	ds_read_b64_tr_b16 v[66:67], v247 offset:58368
	ds_read_b64_tr_b16 v[68:69], v247 offset:58880
	v_max3_f32 v94, v94, v103, v122
	v_max3_f32 v95, v95, v124, v125
	v_max3_f32 v94, v94, v123, v106
	v_max3_f32 v95, v95, v108, v109
	v_max3_f32 v94, v94, v107, v126
	v_max3_f32 v95, v95, v128, v129
	v_max3_f32 v94, v94, v127, v110
	v_max3_f32 v95, v95, v112, v113
	v_max3_f32 v94, v94, v111, v95
	s_waitcnt lgkmcnt(6)
	v_mfma_f32_32x32x16_bf16 v[50:65], v[158:161], v[70:73], v[50:65]
	ds_read_b64_tr_b16 v[70:71], v247 offset:61440
	ds_read_b64_tr_b16 v[72:73], v247 offset:61952
	v_mov_b32_e32 v95, v94
	s_nop 1
	v_permlane32_swap_b32_e32 v94, v95
	v_max_f32_e32 v95, v95, v95
	v_max_f32_e32 v94, v94, v94
	v_max_f32_e32 v94, v94, v95
	v_cmp_lt_f32_e32 vcc, s93, v94
	s_cmp_lg_u64 vcc, 0
	v_add_f32_e32 v190, v250, v86
	s_cselect_b64 s[36:37], -1, 0
	s_cbranch_vccnz .LBB0_1317
.LBB0_1310:
	s_waitcnt lgkmcnt(6)
	v_mfma_f32_32x32x16_bf16 v[50:65], v[154:157], v[74:77], v[50:65]
	v_exp_f32_e32 v114, v114
	v_exp_f32_e32 v115, v115
	v_exp_f32_e32 v116, v116
	ds_read_b64_tr_b16 v[74:75], v247 offset:62464
	ds_read_b64_tr_b16 v[76:77], v247 offset:62976
	s_waitcnt lgkmcnt(6)
	v_mfma_f32_32x32x16_bf16 v[34:49], v[158:161], v[78:81], v[34:49]
	v_exp_f32_e32 v117, v117
	v_exp_f32_e32 v118, v118
	v_exp_f32_e32 v119, v119
	ds_read_b64_tr_b16 v[78:79], v247 offset:51200
	ds_read_b64_tr_b16 v[80:81], v247 offset:51712
	s_waitcnt lgkmcnt(6)
	v_mfma_f32_32x32x16_bf16 v[34:49], v[154:157], v[66:69], v[34:49]
	v_exp_f32_e32 v120, v120
	v_exp_f32_e32 v121, v121
	v_exp_f32_e32 v122, v122
	ds_read_b64_tr_b16 v[82:83], v247 offset:52224
	ds_read_b64_tr_b16 v[84:85], v247 offset:52736
	s_waitcnt lgkmcnt(6)
	v_mfma_f32_32x32x16_bf16 v[2:17], v[158:161], v[70:73], v[2:17]
	v_exp_f32_e32 v123, v123
	v_exp_f32_e32 v124, v124
	v_exp_f32_e32 v125, v125
	ds_read_b64_tr_b16 v[86:87], v247 offset:55296
	ds_read_b64_tr_b16 v[88:89], v247 offset:55808
	s_waitcnt lgkmcnt(6)
	v_mfma_f32_32x32x16_bf16 v[2:17], v[154:157], v[74:77], v[2:17]
	v_exp_f32_e32 v126, v126
	v_exp_f32_e32 v127, v127
	v_exp_f32_e32 v128, v128
	ds_read_b64_tr_b16 v[74:75], v247 offset:56320
	ds_read_b64_tr_b16 v[76:77], v247 offset:56832
	v_add_u32_e32 v90, s29, v245
	ds_read_b128 v[70:73], v90
	ds_read_b128 v[66:69], v90 offset:512
	s_waitcnt lgkmcnt(8)
	v_mfma_f32_32x32x16_bf16 v[18:33], v[138:141], v[78:81], v[18:33]
	v_exp_f32_e32 v129, v129
	v_exp_f32_e32 v98, v98
	v_exp_f32_e32 v99, v99
	ds_read_b64_tr_b16 v[78:79], v247 offset:59392
	ds_read_b64_tr_b16 v[80:81], v247 offset:59904
	ds_read_b128 v[182:185], v90 offset:2048
	ds_read_b128 v[174:177], v90 offset:2560
	s_waitcnt lgkmcnt(10)
	v_mfma_f32_32x32x16_bf16 v[18:33], v[130:133], v[82:85], v[18:33]
	v_exp_f32_e32 v100, v100
	v_exp_f32_e32 v101, v101
	ds_read_b64_tr_b16 v[82:83], v247 offset:60416
	ds_read_b64_tr_b16 v[84:85], v247 offset:60928
	ds_read_b128 v[178:181], v90 offset:4096
	ds_read_b128 v[166:169], v90 offset:4608
	s_waitcnt lgkmcnt(12)
	v_mfma_f32_32x32x16_bf16 v[50:65], v[138:141], v[86:89], v[50:65]
	v_exp_f32_e32 v102, v102
	v_exp_f32_e32 v103, v103
	ds_read_b64_tr_b16 v[86:87], v247 offset:63488
	ds_read_b64_tr_b16 v[88:89], v247 offset:64000
	ds_read_b128 v[170:173], v90 offset:6144
	ds_read_b128 v[162:165], v90 offset:6656
	s_waitcnt lgkmcnt(14)
	v_mfma_f32_32x32x16_bf16 v[50:65], v[130:133], v[74:77], v[50:65]
	v_exp_f32_e32 v104, v104
	v_exp_f32_e32 v105, v105
	ds_read_b64_tr_b16 v[74:75], v247 offset:64512
	ds_read_b64_tr_b16 v[76:77], v247 offset:65024
	s_waitcnt lgkmcnt(12)
	v_mfma_f32_32x32x16_bf16 v[34:49], v[138:141], v[78:81], v[34:49]
	v_exp_f32_e32 v106, v106
	v_exp_f32_e32 v107, v107
	s_waitcnt lgkmcnt(8)
	v_mfma_f32_32x32x16_bf16 v[34:49], v[130:133], v[82:85], v[34:49]
	v_exp_f32_e32 v108, v108
	v_exp_f32_e32 v109, v109
	s_waitcnt lgkmcnt(4)
	v_mfma_f32_32x32x16_bf16 v[2:17], v[138:141], v[86:89], v[2:17]
	v_exp_f32_e32 v110, v110
	v_exp_f32_e32 v111, v111
	s_waitcnt lgkmcnt(0)
	v_mfma_f32_32x32x16_bf16 v[2:17], v[130:133], v[74:77], v[2:17]
	v_exp_f32_e32 v112, v112
	v_exp_f32_e32 v113, v113
	s_waitcnt vmcnt(4) lgkmcnt(0)
	s_barrier
	s_andn2_b64 vcc, exec, s[36:37]
	s_cbranch_vccnz .LBB0_1312
	s_waitcnt lgkmcnt(0)
	ds_read_b128 v[74:77], v213 offset:96
	ds_read_b128 v[78:81], v213 offset:64
	ds_read_b128 v[82:85], v213 offset:32
	ds_read_b128 v[86:89], v213
	s_waitcnt lgkmcnt(3)
	v_pk_mul_f32 v[30:31], v[30:31], v[74:75]
	s_waitcnt lgkmcnt(2)
	v_pk_mul_f32 v[26:27], v[26:27], v[78:79]
	s_waitcnt lgkmcnt(1)
	v_pk_mul_f32 v[22:23], v[22:23], v[82:83]
	v_pk_mul_f32 v[32:33], v[32:33], v[76:77]
	v_pk_mul_f32 v[28:29], v[28:29], v[80:81]
	v_pk_mul_f32 v[24:25], v[24:25], v[84:85]
	s_waitcnt lgkmcnt(0)
	v_pk_mul_f32 v[20:21], v[20:21], v[88:89]
	v_pk_mul_f32 v[18:19], v[18:19], v[86:87]
	v_pk_mul_f32 v[62:63], v[62:63], v[74:75]
	v_pk_mul_f32 v[58:59], v[58:59], v[78:79]
	v_pk_mul_f32 v[54:55], v[54:55], v[82:83]
	v_pk_mul_f32 v[64:65], v[64:65], v[76:77]
	v_pk_mul_f32 v[60:61], v[60:61], v[80:81]
	v_pk_mul_f32 v[56:57], v[56:57], v[84:85]
	v_pk_mul_f32 v[52:53], v[52:53], v[88:89]
	v_pk_mul_f32 v[50:51], v[50:51], v[86:87]
	v_pk_mul_f32 v[46:47], v[46:47], v[74:75]
	v_pk_mul_f32 v[42:43], v[42:43], v[78:79]
	v_pk_mul_f32 v[38:39], v[38:39], v[82:83]
	v_pk_mul_f32 v[48:49], v[48:49], v[76:77]
	v_pk_mul_f32 v[44:45], v[44:45], v[80:81]
	v_pk_mul_f32 v[40:41], v[40:41], v[84:85]
	v_pk_mul_f32 v[36:37], v[36:37], v[88:89]
	v_pk_mul_f32 v[34:35], v[34:35], v[86:87]
	v_pk_mul_f32 v[14:15], v[14:15], v[74:75]
	v_pk_mul_f32 v[10:11], v[10:11], v[78:79]
	v_pk_mul_f32 v[6:7], v[6:7], v[82:83]
	v_pk_mul_f32 v[16:17], v[16:17], v[76:77]
	v_pk_mul_f32 v[12:13], v[12:13], v[80:81]
	v_pk_mul_f32 v[8:9], v[8:9], v[84:85]
	v_pk_mul_f32 v[4:5], v[4:5], v[88:89]
	v_pk_mul_f32 v[2:3], v[2:3], v[86:87]
.LBB0_1312:
	s_add_i32 s27, s29, 0x4000
	s_cmpk_lg_u32 s29, 0x8000
	s_cselect_b32 s27, s27, 0
	v_mfma_f32_32x32x16_bf16 v[82:97], v[70:73], v[150:153], v[218:233]
	v_add_f32_e32 v74, v114, v115
	v_add_f32_e32 v74, v116, v74
	v_add_f32_e32 v74, v117, v74
	v_add_f32_e32 v74, v118, v74
	v_add_u32_e32 v247, s91, v246
	v_add_f32_e32 v74, v119, v74
	v_cvt_pk_bf16_f32 v158, v114, v115
	v_cvt_pk_bf16_f32 v159, v116, v117
	s_nop 0
	v_add_f32_e32 v70, v120, v74
	v_add_f32_e32 v70, v121, v70
	v_add_f32_e32 v70, v122, v70
	v_add_f32_e32 v114, v123, v70
	v_mfma_f32_32x32x16_bf16 v[66:81], v[66:69], v[150:153], v[218:233]
	v_cvt_pk_bf16_f32 v160, v118, v119
	v_cvt_pk_bf16_f32 v161, v120, v121
	v_mfma_f32_32x32x16_bf16 v[82:97], v[182:185], v[146:149], v[82:97]
	v_add_f32_e32 v114, v124, v114
	v_add_f32_e32 v114, v125, v114
	v_add_f32_e32 v114, v126, v114
	v_add_f32_e32 v114, v127, v114
	v_cvt_pk_bf16_f32 v154, v122, v123
	v_cvt_pk_bf16_f32 v155, v124, v125
	v_mfma_f32_32x32x16_bf16 v[66:81], v[174:177], v[146:149], v[66:81]
	v_add_f32_e32 v114, v128, v114
	v_add_f32_e32 v114, v129, v114
	v_add_f32_e32 v114, v98, v114
	v_add_f32_e32 v118, v99, v114
	v_cvt_pk_bf16_f32 v156, v126, v127
	v_cvt_pk_bf16_f32 v157, v128, v129
	ds_read_b64_tr_b16 v[114:115], v247 offset:49152
	ds_read_b64_tr_b16 v[116:117], v247 offset:49664
	v_mfma_f32_32x32x16_bf16 v[82:97], v[178:181], v[142:145], v[82:97]
	v_add_f32_e32 v118, v100, v118
	v_add_f32_e32 v118, v101, v118
	v_add_f32_e32 v118, v102, v118
	v_add_f32_e32 v118, v103, v118
	v_cvt_pk_bf16_f32 v138, v98, v99
	v_cvt_pk_bf16_f32 v139, v100, v101
	ds_read_b64_tr_b16 v[98:99], v247 offset:50176
	ds_read_b64_tr_b16 v[100:101], v247 offset:50688
	s_mov_b64 s[30:31], 0x1dd40000
	v_lshl_add_u64 v[124:125], v[188:189], 0, s[30:31]
	s_add_i32 s36, s29, s25
	s_mov_b32 s30, m0
	s_mov_b32 m0, s36
	s_nop 0
	global_load_lds_dwordx4 v[124:125], off
	s_mov_b32 m0, s30
	v_mfma_f32_32x32x16_bf16 v[66:81], v[166:169], v[142:145], v[66:81]
	v_add_f32_e32 v118, v104, v118
	v_add_f32_e32 v118, v105, v118
	v_add_f32_e32 v118, v106, v118
	v_add_f32_e32 v118, v107, v118
	v_cvt_pk_bf16_f32 v140, v102, v103
	v_cvt_pk_bf16_f32 v141, v104, v105
	ds_read_b64_tr_b16 v[102:103], v247 offset:53248
	ds_read_b64_tr_b16 v[104:105], v247 offset:53760
	s_mov_b64 s[30:31], 0x1dd40080
	v_lshl_add_u64 v[124:125], v[188:189], 0, s[30:31]
	s_add_i32 s30, s36, 0x2000
	s_mov_b32 s31, m0
	s_mov_b32 m0, s30
	s_nop 0
	global_load_lds_dwordx4 v[124:125], off
	s_mov_b32 m0, s31
	v_mfma_f32_32x32x16_bf16 v[82:97], v[170:173], v[134:137], v[82:97]
	v_add_f32_e32 v118, v108, v118
	v_add_f32_e32 v118, v109, v118
	v_add_f32_e32 v118, v110, v118
	v_add_f32_e32 v118, v111, v118
	v_cvt_pk_bf16_f32 v130, v106, v107
	v_cvt_pk_bf16_f32 v131, v108, v109
	ds_read_b64_tr_b16 v[106:107], v247 offset:54272
	ds_read_b64_tr_b16 v[108:109], v247 offset:54784
	s_mov_b64 s[30:31], 0x25cc0000
	v_lshl_add_u64 v[124:125], v[186:187], 0, s[30:31]
	s_add_i32 s36, s27, s24
	s_mov_b32 s30, m0
	s_mov_b32 m0, s36
	s_nop 0
	global_load_lds_dwordx4 v[124:125], off
	s_mov_b32 m0, s30
	v_mfma_f32_32x32x16_bf16 v[66:81], v[162:165], v[134:137], v[66:81]
	v_add_f32_e32 v118, v112, v118
	v_add_f32_e32 v118, v113, v118
	v_add_f32_e32 v118, 0, v118
	v_cvt_pk_bf16_f32 v132, v110, v111
	v_cvt_pk_bf16_f32 v133, v112, v113
	s_mov_b64 s[30:31], 0x25cc0080
	v_lshl_add_u64 v[124:125], v[186:187], 0, s[30:31]
	s_add_i32 s30, s36, 0x2000
	s_mov_b32 s31, m0
	s_mov_b32 m0, s30
	s_nop 0
	global_load_lds_dwordx4 v[124:125], off
	s_mov_b32 m0, s31
	s_waitcnt lgkmcnt(6)
	v_mfma_f32_32x32x16_bf16 v[18:33], v[158:161], v[114:117], v[18:33]
	ds_read_b64_tr_b16 v[110:111], v247 offset:57344
	ds_read_b64_tr_b16 v[112:113], v247 offset:57856
	v_max_f32_e32 v122, v83, v83
	v_max_f32_e32 v123, v82, v82
	v_max_f32_e32 v122, v123, v122
	v_max3_f32 v123, v84, v85, v67
	v_max3_f32 v122, v122, v66, v68
	v_max3_f32 v122, v122, v69, v86
	v_max3_f32 v123, v123, v88, v89
	v_max3_f32 v122, v122, v87, v70
	v_max3_f32 v123, v123, v72, v73
	s_waitcnt lgkmcnt(6)
	v_mfma_f32_32x32x16_bf16 v[18:33], v[154:157], v[98:101], v[18:33]
	ds_read_b64_tr_b16 v[98:99], v247 offset:58368
	ds_read_b64_tr_b16 v[100:101], v247 offset:58880
	v_max3_f32 v122, v122, v71, v90
	v_max3_f32 v123, v123, v92, v93
	v_max3_f32 v122, v122, v91, v74
	v_max3_f32 v123, v123, v76, v77
	v_max3_f32 v122, v122, v75, v94
	v_max3_f32 v123, v123, v96, v97
	v_max3_f32 v122, v122, v95, v78
	v_max3_f32 v123, v123, v80, v81
	v_max3_f32 v122, v122, v79, v123
	s_waitcnt lgkmcnt(6)
	v_mfma_f32_32x32x16_bf16 v[50:65], v[158:161], v[102:105], v[50:65]
	ds_read_b64_tr_b16 v[102:103], v247 offset:61440
	ds_read_b64_tr_b16 v[104:105], v247 offset:61952
	v_mov_b32_e32 v123, v122
	s_nop 1
	v_permlane32_swap_b32_e32 v122, v123
	v_max_f32_e32 v123, v123, v123
	v_max_f32_e32 v122, v122, v122
	v_max_f32_e32 v122, v122, v123
	v_cmp_lt_f32_e32 vcc, s93, v122
	s_cmp_lg_u64 vcc, 0
	v_add_f32_e32 v250, v190, v118
	s_cselect_b64 s[36:37], -1, 0
	s_cbranch_vccnz .LBB0_1320
.LBB0_1313:
	s_waitcnt lgkmcnt(6)
	v_mfma_f32_32x32x16_bf16 v[50:65], v[154:157], v[106:109], v[50:65]
	v_exp_f32_e32 v82, v82
	v_exp_f32_e32 v83, v83
	v_exp_f32_e32 v84, v84
	ds_read_b64_tr_b16 v[106:107], v247 offset:62464
	ds_read_b64_tr_b16 v[108:109], v247 offset:62976
	s_waitcnt lgkmcnt(6)
	v_mfma_f32_32x32x16_bf16 v[34:49], v[158:161], v[110:113], v[34:49]
	v_exp_f32_e32 v85, v85
	v_exp_f32_e32 v86, v86
	v_exp_f32_e32 v87, v87
	ds_read_b64_tr_b16 v[110:111], v247 offset:51200
	ds_read_b64_tr_b16 v[112:113], v247 offset:51712
	s_waitcnt lgkmcnt(6)
	v_mfma_f32_32x32x16_bf16 v[34:49], v[154:157], v[98:101], v[34:49]
	v_exp_f32_e32 v88, v88
	v_exp_f32_e32 v89, v89
	v_exp_f32_e32 v90, v90
	ds_read_b64_tr_b16 v[98:99], v247 offset:52224
	ds_read_b64_tr_b16 v[100:101], v247 offset:52736
	s_waitcnt lgkmcnt(6)
	v_mfma_f32_32x32x16_bf16 v[2:17], v[158:161], v[102:105], v[2:17]
	v_exp_f32_e32 v91, v91
	v_exp_f32_e32 v92, v92
	v_exp_f32_e32 v93, v93
	ds_read_b64_tr_b16 v[102:103], v247 offset:55296
	ds_read_b64_tr_b16 v[104:105], v247 offset:55808
	s_waitcnt lgkmcnt(6)
	v_mfma_f32_32x32x16_bf16 v[2:17], v[154:157], v[106:109], v[2:17]
	v_exp_f32_e32 v94, v94
	v_exp_f32_e32 v95, v95
	v_exp_f32_e32 v96, v96
	ds_read_b64_tr_b16 v[106:107], v247 offset:56320
	ds_read_b64_tr_b16 v[108:109], v247 offset:56832
	v_add_u32_e32 v114, s27, v245
	ds_read_b128 v[190:193], v114
	ds_read_b128 v[182:185], v114 offset:512
	s_waitcnt lgkmcnt(8)
	v_mfma_f32_32x32x16_bf16 v[18:33], v[138:141], v[110:113], v[18:33]
	v_exp_f32_e32 v97, v97
	v_exp_f32_e32 v66, v66
	v_exp_f32_e32 v67, v67
	ds_read_b64_tr_b16 v[110:111], v247 offset:59392
	ds_read_b64_tr_b16 v[112:113], v247 offset:59904
	ds_read_b128 v[186:189], v114 offset:2048
	ds_read_b128 v[178:181], v114 offset:2560
	s_waitcnt lgkmcnt(10)
	v_mfma_f32_32x32x16_bf16 v[18:33], v[130:133], v[98:101], v[18:33]
	v_exp_f32_e32 v68, v68
	v_exp_f32_e32 v69, v69
	ds_read_b64_tr_b16 v[98:99], v247 offset:60416
	ds_read_b64_tr_b16 v[100:101], v247 offset:60928
	ds_read_b128 v[174:177], v114 offset:4096
	ds_read_b128 v[170:173], v114 offset:4608
	s_waitcnt lgkmcnt(12)
	v_mfma_f32_32x32x16_bf16 v[50:65], v[138:141], v[102:105], v[50:65]
	v_exp_f32_e32 v70, v70
	v_exp_f32_e32 v71, v71
	ds_read_b64_tr_b16 v[102:103], v247 offset:63488
	ds_read_b64_tr_b16 v[104:105], v247 offset:64000
	ds_read_b128 v[166:169], v114 offset:6144
	ds_read_b128 v[162:165], v114 offset:6656
	s_waitcnt lgkmcnt(14)
	v_mfma_f32_32x32x16_bf16 v[50:65], v[130:133], v[106:109], v[50:65]
	v_exp_f32_e32 v72, v72
	v_exp_f32_e32 v73, v73
	ds_read_b64_tr_b16 v[106:107], v247 offset:64512
	ds_read_b64_tr_b16 v[108:109], v247 offset:65024
	s_waitcnt lgkmcnt(12)
	v_mfma_f32_32x32x16_bf16 v[34:49], v[138:141], v[110:113], v[34:49]
	v_exp_f32_e32 v74, v74
	v_exp_f32_e32 v75, v75
	s_waitcnt lgkmcnt(8)
	v_mfma_f32_32x32x16_bf16 v[34:49], v[130:133], v[98:101], v[34:49]
	v_exp_f32_e32 v76, v76
	v_exp_f32_e32 v77, v77
	s_waitcnt lgkmcnt(4)
	v_mfma_f32_32x32x16_bf16 v[2:17], v[138:141], v[102:105], v[2:17]
	v_exp_f32_e32 v78, v78
	v_exp_f32_e32 v79, v79
	s_waitcnt lgkmcnt(0)
	v_mfma_f32_32x32x16_bf16 v[2:17], v[130:133], v[106:109], v[2:17]
	v_exp_f32_e32 v80, v80
	v_exp_f32_e32 v81, v81
	s_waitcnt vmcnt(4) lgkmcnt(0)
	s_barrier
	s_andn2_b64 vcc, exec, s[36:37]
	s_cbranch_vccnz .LBB0_1315
	s_waitcnt lgkmcnt(0)
	ds_read_b128 v[98:101], v213 offset:96
	ds_read_b128 v[102:105], v213 offset:64
	ds_read_b128 v[106:109], v213 offset:32
	ds_read_b128 v[110:113], v213
	s_waitcnt lgkmcnt(3)
	v_pk_mul_f32 v[30:31], v[30:31], v[98:99]
	s_waitcnt lgkmcnt(2)
	v_pk_mul_f32 v[26:27], v[26:27], v[102:103]
	s_waitcnt lgkmcnt(1)
	v_pk_mul_f32 v[22:23], v[22:23], v[106:107]
	v_pk_mul_f32 v[32:33], v[32:33], v[100:101]
	v_pk_mul_f32 v[28:29], v[28:29], v[104:105]
	v_pk_mul_f32 v[24:25], v[24:25], v[108:109]
	s_waitcnt lgkmcnt(0)
	v_pk_mul_f32 v[20:21], v[20:21], v[112:113]
	v_pk_mul_f32 v[18:19], v[18:19], v[110:111]
	v_pk_mul_f32 v[62:63], v[62:63], v[98:99]
	v_pk_mul_f32 v[58:59], v[58:59], v[102:103]
	v_pk_mul_f32 v[54:55], v[54:55], v[106:107]
	v_pk_mul_f32 v[64:65], v[64:65], v[100:101]
	v_pk_mul_f32 v[60:61], v[60:61], v[104:105]
	v_pk_mul_f32 v[56:57], v[56:57], v[108:109]
	v_pk_mul_f32 v[52:53], v[52:53], v[112:113]
	v_pk_mul_f32 v[50:51], v[50:51], v[110:111]
	v_pk_mul_f32 v[46:47], v[46:47], v[98:99]
	v_pk_mul_f32 v[42:43], v[42:43], v[102:103]
	v_pk_mul_f32 v[38:39], v[38:39], v[106:107]
	v_pk_mul_f32 v[48:49], v[48:49], v[100:101]
	v_pk_mul_f32 v[44:45], v[44:45], v[104:105]
	v_pk_mul_f32 v[40:41], v[40:41], v[108:109]
	v_pk_mul_f32 v[36:37], v[36:37], v[112:113]
	v_pk_mul_f32 v[34:35], v[34:35], v[110:111]
	v_pk_mul_f32 v[14:15], v[14:15], v[98:99]
	v_pk_mul_f32 v[10:11], v[10:11], v[102:103]
	v_pk_mul_f32 v[6:7], v[6:7], v[106:107]
	v_pk_mul_f32 v[16:17], v[16:17], v[100:101]
	v_pk_mul_f32 v[12:13], v[12:13], v[104:105]
	v_pk_mul_f32 v[8:9], v[8:9], v[108:109]
	v_pk_mul_f32 v[4:5], v[4:5], v[112:113]
	v_pk_mul_f32 v[2:3], v[2:3], v[110:111]

.LBB0_1317:
	v_max_f32_e32 v94, v94, v94
	v_max_f32_e32 v95, 0, v94
	v_exp_f32_e64 v94, -v95
	s_and_saveexec_b64 s[54:55], s[38:39]
	ds_write_b32 v239, v94
	s_or_b64 exec, exec, s[54:55]
	v_add_f32_e32 v243, v243, v95
	v_mul_f32_e32 v190, v190, v94
	v_sub_f32_e32 v114, v114, v95
	v_sub_f32_e32 v115, v115, v95
	v_sub_f32_e32 v116, v116, v95
	v_sub_f32_e32 v117, v117, v95
	v_sub_f32_e32 v118, v118, v95
	v_sub_f32_e32 v119, v119, v95
	v_sub_f32_e32 v120, v120, v95
	v_sub_f32_e32 v121, v121, v95
	v_sub_f32_e32 v122, v122, v95
	v_sub_f32_e32 v123, v123, v95
	v_sub_f32_e32 v124, v124, v95
	v_sub_f32_e32 v125, v125, v95
	v_sub_f32_e32 v126, v126, v95
	v_sub_f32_e32 v127, v127, v95
	v_sub_f32_e32 v128, v128, v95
	v_sub_f32_e32 v129, v129, v95
	v_sub_f32_e32 v98, v98, v95
	v_sub_f32_e32 v99, v99, v95
	v_sub_f32_e32 v100, v100, v95
	v_sub_f32_e32 v101, v101, v95
	v_sub_f32_e32 v102, v102, v95
	v_sub_f32_e32 v103, v103, v95
	v_sub_f32_e32 v104, v104, v95
	v_sub_f32_e32 v105, v105, v95
	v_sub_f32_e32 v106, v106, v95
	v_sub_f32_e32 v107, v107, v95
	v_sub_f32_e32 v108, v108, v95
	v_sub_f32_e32 v109, v109, v95
	v_sub_f32_e32 v110, v110, v95
	v_sub_f32_e32 v111, v111, v95
	v_sub_f32_e32 v112, v112, v95
	v_sub_f32_e32 v113, v113, v95
	v_sub_f32_e32 v218, v218, v95
	v_sub_f32_e32 v219, v219, v95
	v_sub_f32_e32 v220, v220, v95
	v_sub_f32_e32 v221, v221, v95
	v_sub_f32_e32 v222, v222, v95
	v_sub_f32_e32 v223, v223, v95
	v_sub_f32_e32 v224, v224, v95
	v_sub_f32_e32 v225, v225, v95
	v_sub_f32_e32 v226, v226, v95
	v_sub_f32_e32 v227, v227, v95
	v_sub_f32_e32 v228, v228, v95
	v_sub_f32_e32 v229, v229, v95
	v_sub_f32_e32 v230, v230, v95
	v_sub_f32_e32 v231, v231, v95
	v_sub_f32_e32 v232, v232, v95
	v_sub_f32_e32 v233, v233, v95
	s_branch .LBB0_1310
.LBB0_1320:
	v_max_f32_e32 v122, v122, v122
	v_max_f32_e32 v123, 0, v122
	v_exp_f32_e64 v122, -v123
	s_and_saveexec_b64 s[54:55], s[38:39]
	ds_write_b32 v239, v122
	s_or_b64 exec, exec, s[54:55]
	v_add_f32_e32 v243, v243, v123
	v_mul_f32_e32 v250, v250, v122
	v_sub_f32_e32 v82, v82, v123
	v_sub_f32_e32 v83, v83, v123
	v_sub_f32_e32 v84, v84, v123
	v_sub_f32_e32 v85, v85, v123
	v_sub_f32_e32 v86, v86, v123
	v_sub_f32_e32 v87, v87, v123
	v_sub_f32_e32 v88, v88, v123
	v_sub_f32_e32 v89, v89, v123
	v_sub_f32_e32 v90, v90, v123
	v_sub_f32_e32 v91, v91, v123
	v_sub_f32_e32 v92, v92, v123
	v_sub_f32_e32 v93, v93, v123
	v_sub_f32_e32 v94, v94, v123
	v_sub_f32_e32 v95, v95, v123
	v_sub_f32_e32 v96, v96, v123
	v_sub_f32_e32 v97, v97, v123
	v_sub_f32_e32 v66, v66, v123
	v_sub_f32_e32 v67, v67, v123
	v_sub_f32_e32 v68, v68, v123
	v_sub_f32_e32 v69, v69, v123
	v_sub_f32_e32 v70, v70, v123
	v_sub_f32_e32 v71, v71, v123
	v_sub_f32_e32 v72, v72, v123
	v_sub_f32_e32 v73, v73, v123
	v_sub_f32_e32 v74, v74, v123
	v_sub_f32_e32 v75, v75, v123
	v_sub_f32_e32 v76, v76, v123
	v_sub_f32_e32 v77, v77, v123
	v_sub_f32_e32 v78, v78, v123
	v_sub_f32_e32 v79, v79, v123
	v_sub_f32_e32 v80, v80, v123
	v_sub_f32_e32 v81, v81, v123
	v_sub_f32_e32 v218, v218, v123
	v_sub_f32_e32 v219, v219, v123
	v_sub_f32_e32 v220, v220, v123
	v_sub_f32_e32 v221, v221, v123
	v_sub_f32_e32 v222, v222, v123
	v_sub_f32_e32 v223, v223, v123
	v_sub_f32_e32 v224, v224, v123
	v_sub_f32_e32 v225, v225, v123
	v_sub_f32_e32 v226, v226, v123
	v_sub_f32_e32 v227, v227, v123
	v_sub_f32_e32 v228, v228, v123
	v_sub_f32_e32 v229, v229, v123
	v_sub_f32_e32 v230, v230, v123
	v_sub_f32_e32 v231, v231, v123
	v_sub_f32_e32 v232, v232, v123
	v_sub_f32_e32 v233, v233, v123
	s_branch .LBB0_1313
